# v15: + scan P-tile masking as straight-line compare/select; ln(x)=log2(x)*ln2 as a single f32 multiply in the GLA gate (drops the compensated-product tail of the logf expansion)
# speedup vs baseline: 1.0265x; 1.0031x over previous
; #define LAUNDER(t) const int t = opaque_tid(wv)
; #define LBAR() do { asm volatile("s_waitcnt lgkmcnt(0)" ::: "memory"); __builtin_amdgcn_s_barrier(); asm volatile("" ::: "memory"); } while (0)
; __device__ __forceinline__ void phase_scan(const bf16_t* QK, const bf16_t* V, const float* GLR, bf16_t* OFW, const float* wgate, const float* bgate, char* lds, int wv,
;                                            bf16_t* Z, const float* gn, unsigned long long* X, unsigned tag) {
;     ...
;                     LAUNDER(t); const int ln = t & 63, r32 = ln & 31, hi = ln >> 5, cb = wid >> 2, db = wid & 3, d = db * 32 + r32;
;                     f32x4 ar[4];
; #pragma unroll
;                     for (int i = 0; i < 4; ++i) ar[i] = *(const f32x4*)(lds + OFF_GLR + (cb * 32 + r32) * 64 + i * 16);
;                     asm volatile("s_waitcnt lgkmcnt(0)" ::: "memory"); __builtin_amdgcn_sched_barrier(0);
;                     f32x16 pa;
; #pragma unroll
;                     for (int r = 0; r < 16; ++r) pa[r] = bgv;
; #pragma unroll
;                     for (int kk = 0; kk < 8; ++kk) { const float a = hi ? ar[kk >> 1][2 * (kk & 1) + 1] : ar[kk >> 1][2 * (kk & 1)];
;                         pa = __builtin_amdgcn_mfma_f32_32x32x2f32(a, wgb[kk], pa, 0, 0, 0); }
;                     float lgv[16], pl[16];
; #pragma unroll
;                     for (int r = 0; r < 16; ++r) { const float pre = pa[r]; lgv[r] = -(fmaxf(-pre, 0.f) + __logf(1.f + __expf(-fabsf(pre)))) * (0.0625f * 1.4426950408889634f); }
; #pragma unroll
;                     for (int k = 0; k < 4; ++k) { pl[4 * k] = lgv[4 * k]; pl[4 * k + 1] = pl[4 * k] + lgv[4 * k + 1]; pl[4 * k + 2] = pl[4 * k + 1] + lgv[4 * k + 2]; pl[4 * k + 3] = pl[4 * k + 2] + lgv[4 * k + 3]; }
; #pragma unroll
;                     for (int k = 0; k < 4; ++k) *(float*)(lds + OFF_P + ((cb * 8 + 2 * k + hi) * 128 + d) * 4) = pl[4 * k + 3];
;                     LBAR();
.LBB0_523:
	s_nop 1
	v_mov_b32_e32 v80, v233
	s_nop 0
	v_and_b32_e32 v97, 31, v80
	v_lshl_add_u32 v81, v97, 6, s29
	ds_read_b128 v[98:101], v81
	ds_read_b128 v[102:105], v81 offset:16
	ds_read_b128 v[106:109], v81 offset:32
	ds_read_b128 v[160:163], v81 offset:48
	s_waitcnt lgkmcnt(0)
	v_bfe_u32 v96, v80, 5, 1
	v_and_b32_e32 v80, 32, v80
	v_cmp_ne_u32_e64 s[6:7], 0, v80
	v_cmp_eq_u32_e32 vcc, 0, v96
	s_waitcnt lgkmcnt(3)
	v_cndmask_b32_e64 v110, v98, v99, s[6:7]
	s_nop 1
	v_mfma_f32_32x32x2_f32 v[80:95], v110, v243, v[0:15]
	v_cndmask_b32_e64 v110, 3, 2, vcc
	v_cmp_eq_u32_e64 s[8:9], 1, v110
	s_nop 1
	v_cndmask_b32_e64 v98, v98, v99, s[8:9]
	v_cndmask_b32_e32 v98, v98, v100, vcc
	v_cndmask_b32_e64 v98, v98, v101, s[6:7]
	s_nop 1
	v_mfma_f32_32x32x2_f32 v[80:95], v98, v237, v[80:95]
	s_waitcnt lgkmcnt(2)
	v_cndmask_b32_e64 v98, v102, v103, s[6:7]
	s_nop 1
	v_mfma_f32_32x32x2_f32 v[80:95], v98, v238, v[80:95]
	v_cndmask_b32_e64 v98, v102, v103, s[8:9]
	v_cndmask_b32_e32 v98, v98, v104, vcc
	v_cndmask_b32_e64 v98, v98, v105, s[6:7]
	s_nop 1
	v_mfma_f32_32x32x2_f32 v[80:95], v98, v239, v[80:95]
	s_waitcnt lgkmcnt(1)
	v_cndmask_b32_e64 v98, v106, v107, s[6:7]
	s_nop 1
	v_mfma_f32_32x32x2_f32 v[80:95], v98, v240, v[80:95]
	v_cndmask_b32_e64 v98, v106, v107, s[8:9]
	v_cndmask_b32_e32 v98, v98, v108, vcc
	v_cndmask_b32_e64 v98, v98, v109, s[6:7]
	s_nop 1
	v_mfma_f32_32x32x2_f32 v[80:95], v98, v241, v[80:95]
	s_waitcnt lgkmcnt(0)
	v_cndmask_b32_e64 v98, v160, v161, s[6:7]
	s_nop 1
	v_mfma_f32_32x32x2_f32 v[80:95], v98, v242, v[80:95]
	v_cndmask_b32_e64 v98, v160, v161, s[8:9]
	v_cndmask_b32_e32 v98, v98, v162, vcc
	v_cndmask_b32_e64 v98, v98, v163, s[6:7]
	s_nop 1
	v_mfma_f32_32x32x2_f32 v[80:95], v98, v244, v[80:95]
	s_nop 15
	s_nop 1
	v_max_f32_e64 v98, -v80, 0
	v_mul_f32_e64 v80, |v80|, s0
	v_exp_f32_e32 v80, v80
	s_nop 0
	v_add_f32_e32 v80, 1.0, v80
	v_log_f32_e32 v80, v80
	s_nop 0
	v_mul_f32_e32 v80, 0x3f317217, v80
	v_add_f32_e32 v80, v98, v80
	v_max_f32_e64 v98, -v81, 0
	v_mul_f32_e64 v81, |v81|, s0
	v_exp_f32_e32 v81, v81
	s_nop 0
	v_add_f32_e32 v81, 1.0, v81
	v_log_f32_e32 v81, v81
	s_nop 0
	v_mul_f32_e32 v81, 0x3f317217, v81
	v_max_f32_e64 v99, -v82, 0
	v_mul_f32_e64 v82, |v82|, s0
	v_exp_f32_e32 v82, v82
	v_add_f32_e32 v81, v98, v81
	v_mul_f32_e32 v98, 0xbdb8aa3b, v81
	v_add_f32_e32 v82, 1.0, v82
	v_fmac_f32_e32 v98, 0xbdb8aa3b, v80
	s_nop 0
	v_log_f32_e32 v82, v82
	s_nop 0
	v_mul_f32_e32 v82, 0x3f317217, v82
	v_add_f32_e32 v82, v99, v82
	v_max_f32_e64 v99, -v83, 0
	v_mul_f32_e64 v83, |v83|, s0
	v_exp_f32_e32 v83, v83
	v_fmamk_f32 v168, v82, 0xbdb8aa3b, v98
	v_add_f32_e32 v83, 1.0, v83
	v_log_f32_e32 v83, v83
	s_nop 0
	v_mul_f32_e32 v83, 0x3f317217, v83
	v_add_f32_e32 v83, v99, v83
	v_max_f32_e64 v99, -v84, 0
	v_mul_f32_e64 v84, |v84|, s0
	v_exp_f32_e32 v84, v84
	v_fmamk_f32 v169, v83, 0xbdb8aa3b, v168
	v_add_f32_e32 v84, 1.0, v84
	v_log_f32_e32 v84, v84
	s_nop 0
	v_mul_f32_e32 v84, 0x3f317217, v84
	v_add_f32_e32 v84, v99, v84
	v_max_f32_e64 v99, -v85, 0
	v_mul_f32_e64 v85, |v85|, s0
	v_exp_f32_e32 v85, v85
	s_nop 0
	v_add_f32_e32 v85, 1.0, v85
	v_log_f32_e32 v85, v85
	s_nop 0
	v_mul_f32_e32 v85, 0x3f317217, v85
	v_max_f32_e64 v100, -v86, 0
	v_mul_f32_e64 v86, |v86|, s0
	v_exp_f32_e32 v86, v86
	v_add_f32_e32 v85, v99, v85
	v_mul_f32_e32 v99, 0xbdb8aa3b, v85
	v_add_f32_e32 v86, 1.0, v86
	v_fmac_f32_e32 v99, 0xbdb8aa3b, v84
	s_nop 0
	v_log_f32_e32 v86, v86
	s_nop 0
	v_mul_f32_e32 v86, 0x3f317217, v86
	v_add_f32_e32 v86, v100, v86
	v_max_f32_e64 v100, -v87, 0
	v_mul_f32_e64 v87, |v87|, s0
	v_exp_f32_e32 v87, v87
	v_fmamk_f32 v170, v86, 0xbdb8aa3b, v99
	v_add_f32_e32 v87, 1.0, v87
	v_log_f32_e32 v87, v87
	s_nop 0
	v_mul_f32_e32 v87, 0x3f317217, v87
	v_add_f32_e32 v87, v100, v87
	v_max_f32_e64 v100, -v88, 0
	v_mul_f32_e64 v88, |v88|, s0
	v_exp_f32_e32 v88, v88
	v_fmamk_f32 v171, v87, 0xbdb8aa3b, v170
	v_add_f32_e32 v88, 1.0, v88
	v_log_f32_e32 v88, v88
	s_nop 0
	v_mul_f32_e32 v88, 0x3f317217, v88
	v_add_f32_e32 v88, v100, v88
	v_max_f32_e64 v100, -v89, 0
	v_mul_f32_e64 v89, |v89|, s0
	v_exp_f32_e32 v89, v89
	s_nop 0
	v_add_f32_e32 v89, 1.0, v89
	v_log_f32_e32 v89, v89
	s_nop 0
	v_mul_f32_e32 v89, 0x3f317217, v89
	v_max_f32_e64 v101, -v90, 0
	v_mul_f32_e64 v90, |v90|, s0
	v_exp_f32_e32 v90, v90
	v_add_f32_e32 v89, v100, v89
	v_mul_f32_e32 v100, 0xbdb8aa3b, v89
	v_add_f32_e32 v90, 1.0, v90
	v_fmac_f32_e32 v100, 0xbdb8aa3b, v88
	s_nop 0
	v_log_f32_e32 v90, v90
	s_nop 0
	v_mul_f32_e32 v90, 0x3f317217, v90
	v_add_f32_e32 v101, v101, v90
	v_max_f32_e64 v90, -v91, 0
	v_mul_f32_e64 v91, |v91|, s0
	v_exp_f32_e32 v91, v91
	v_fmamk_f32 v172, v101, 0xbdb8aa3b, v100
	v_add_f32_e32 v91, 1.0, v91
	v_log_f32_e32 v91, v91
	s_nop 0
	v_mul_f32_e32 v91, 0x3f317217, v91
	v_add_f32_e32 v162, v90, v91
	v_mul_f32_e64 v91, |v92|, s0
	v_exp_f32_e32 v91, v91
	v_max_f32_e64 v90, -v92, 0
	v_fmamk_f32 v173, v162, 0xbdb8aa3b, v172
	v_add_f32_e32 v91, 1.0, v91
	v_log_f32_e32 v91, v91
	s_nop 0
	v_mul_f32_e32 v91, 0x3f317217, v91
	v_add_f32_e32 v163, v90, v91
	v_mul_f32_e64 v91, |v93|, s0
	v_exp_f32_e32 v91, v91
	v_max_f32_e64 v90, -v93, 0
	v_add_f32_e32 v91, 1.0, v91
	v_log_f32_e32 v91, v91
	s_nop 0
	v_mul_f32_e32 v91, 0x3f317217, v91
	v_add_f32_e32 v164, v90, v91
	v_mul_f32_e64 v91, |v94|, s0
	v_exp_f32_e32 v91, v91
	v_max_f32_e64 v90, -v94, 0
	v_mul_f32_e32 v165, 0xbdb8aa3b, v164
	v_add_f32_e32 v91, 1.0, v91
	v_fmac_f32_e32 v165, 0xbdb8aa3b, v163
	s_nop 0
	v_log_f32_e32 v91, v91
	s_nop 0
	v_mul_f32_e32 v91, 0x3f317217, v91
	v_add_f32_e32 v166, v90, v91
	v_mul_f32_e64 v91, |v95|, s0
	v_exp_f32_e32 v91, v91
	v_max_f32_e64 v90, -v95, 0
	v_fmamk_f32 v174, v166, 0xbdb8aa3b, v165
	v_add_f32_e32 v91, 1.0, v91
	v_log_f32_e32 v91, v91
	s_nop 0
	v_mul_f32_e32 v91, 0x3f317217, v91
	v_add_f32_e32 v167, v90, v91
	v_or_b32_e32 v90, s53, v97
	v_lshlrev_b32_e32 v97, 2, v90
	v_add_u32_e32 v90, 0, v97
	v_lshlrev_b32_e32 v91, 9, v96
	v_add3_u32 v91, v90, s27, v91
	v_fmamk_f32 v175, v167, 0xbdb8aa3b, v174
	ds_write2st64_b32 v91, v169, v171 offset0:148 offset1:152
	ds_write2st64_b32 v91, v173, v175 offset0:156 offset1:160
	s_waitcnt lgkmcnt(0)
	s_barrier
; __device__ __forceinline__ void phase_scan(const bf16_t* QK, const bf16_t* V, const float* GLR, bf16_t* OFW, const float* wgate, const float* bgate, char* lds, int wv,
;                                            bf16_t* Z, const float* gn, unsigned long long* X, unsigned tag) {
;     ...
;                     float gsv[16];
; #pragma unroll
;                     for (int g = 0; g < 16; ++g) gsv[g] = *(const float*)(lds + OFF_P + (g * 128 + d) * 4);
;                     asm volatile("s_waitcnt lgkmcnt(0)" ::: "memory"); __builtin_amdgcn_sched_barrier(0);
;                     float ex[16]; float run = 0.f;
; #pragma unroll
;                     for (int g = 0; g < 16; ++g) { ex[g] = run; run += gsv[g]; }
;                     const float tot = run;
; #pragma unroll
;                     for (int k = 0; k < 4; ++k) { const float e0 = cb ? ex[8 + 2 * k] : ex[2 * k], e1 = cb ? ex[8 + 2 * k + 1] : ex[2 * k + 1]; const float off = hi ? e1 : e0;
; #pragma unroll
;                         for (int e = 0; e < 4; ++e) { const int r = 4 * k + e; const float bc = dir == 0 ? off + pl[r] : tot - (off + pl[r] - lgv[r]);
;                             *(float*)(lds + OFF_BC + (cb * 32 + e + 8 * k + 4 * hi) * BC_ST + d * 4) = bc; } }
;                     if (cb == 0 && hi == 0) *(float*)(lds + OFF_EBT + d * 4) = __builtin_amdgcn_exp2f(tot);
	ds_read2st64_b32 v[92:93], v90 offset0:148 offset1:150
	ds_read2st64_b32 v[94:95], v90 offset0:152 offset1:154
	ds_read2st64_b32 v[102:103], v90 offset0:156 offset1:158
	ds_read2st64_b32 v[104:105], v90 offset0:160 offset1:162
	ds_read2st64_b32 v[106:107], v90 offset0:164 offset1:166
	ds_read2st64_b32 v[108:109], v90 offset0:168 offset1:170
	ds_read2st64_b32 v[110:111], v90 offset0:172 offset1:174
	ds_read2st64_b32 v[160:161], v90 offset0:176 offset1:178
	s_waitcnt lgkmcnt(0)
	s_waitcnt lgkmcnt(7)
	v_add_f32_e32 v92, 0, v92
	v_add_f32_e32 v93, v92, v93
	s_waitcnt lgkmcnt(6)
	v_add_f32_e32 v94, v93, v94
	v_add_f32_e32 v95, v94, v95
	s_waitcnt lgkmcnt(5)
	v_add_f32_e32 v102, v95, v102
	v_add_f32_e32 v103, v102, v103
	s_waitcnt lgkmcnt(4)
	v_add_f32_e32 v104, v103, v104
	v_add_f32_e32 v105, v104, v105
	s_waitcnt lgkmcnt(3)
	v_add_f32_e32 v106, v105, v106
	v_add_f32_e32 v107, v106, v107
	s_waitcnt lgkmcnt(2)
	v_add_f32_e32 v108, v107, v108
	v_add_f32_e32 v109, v108, v109
	s_waitcnt lgkmcnt(1)
	v_add_f32_e32 v110, v109, v110
	v_lshl_or_b32 v96, v96, 2, s40
	v_cndmask_b32_e64 v105, v105, 0, s[4:5]
	v_cndmask_b32_e64 v92, v106, v92, s[4:5]
	v_add_f32_e32 v111, v110, v111
	s_add_i32 s8, 0, 0x14800
	v_cndmask_b32_e32 v92, v92, v105, vcc
	v_mul_lo_u32 v96, v96, s91
	s_waitcnt lgkmcnt(0)
	v_add_f32_e32 v160, v111, v160
	v_fmamk_f32 v105, v80, 0xbdb8aa3b, v92
	v_add3_u32 v96, s8, v97, v96
	v_add_f32_e32 v97, v98, v92
	v_add_f32_e32 v91, v160, v161
	v_fmamk_f32 v80, v80, 0x3db8aa3b, v105
	v_fmamk_f32 v81, v81, 0x3db8aa3b, v97
	v_sub_f32_e32 v80, v91, v80
	v_sub_f32_e32 v81, v91, v81
	v_cndmask_b32_e64 v80, v80, v105, s[60:61]
	v_cndmask_b32_e64 v81, v81, v97, s[60:61]
	ds_write2_b32 v96, v80, v81 offset1:132
	v_add_f32_e32 v80, v168, v92
	v_fmamk_f32 v81, v82, 0x3db8aa3b, v80
	v_sub_f32_e32 v81, v91, v81
	v_cndmask_b32_e64 v80, v81, v80, s[60:61]
	v_add_f32_e32 v81, v169, v92
	v_fmamk_f32 v82, v83, 0x3db8aa3b, v81
	v_sub_f32_e32 v82, v91, v82
	v_cndmask_b32_e64 v81, v82, v81, s[60:61]
	v_add_u32_e32 v82, 0x400, v96
	ds_write2_b32 v82, v80, v81 offset0:8 offset1:140
	v_cndmask_b32_e64 v80, v107, v93, s[4:5]
	v_cndmask_b32_e64 v81, v108, v94, s[4:5]
	v_cndmask_b32_e32 v80, v81, v80, vcc
	v_fmamk_f32 v81, v84, 0xbdb8aa3b, v80
	v_fmamk_f32 v82, v84, 0x3db8aa3b, v81
	v_sub_f32_e32 v82, v91, v82
	v_cndmask_b32_e64 v81, v82, v81, s[60:61]
	v_add_f32_e32 v82, v99, v80
	v_fmamk_f32 v83, v85, 0x3db8aa3b, v82
	v_sub_f32_e32 v83, v91, v83
	v_cndmask_b32_e64 v82, v83, v82, s[60:61]
	v_add_u32_e32 v83, 0x1000, v96
	ds_write2_b32 v83, v81, v82 offset0:32 offset1:164
	v_add_f32_e32 v81, v170, v80
	v_fmamk_f32 v82, v86, 0x3db8aa3b, v81
	v_sub_f32_e32 v82, v91, v82
	v_add_f32_e32 v80, v171, v80
	v_cndmask_b32_e64 v81, v82, v81, s[60:61]
	v_fmamk_f32 v82, v87, 0x3db8aa3b, v80
	v_sub_f32_e32 v82, v91, v82
	v_cndmask_b32_e64 v80, v82, v80, s[60:61]
	v_add_u32_e32 v82, 0x1400, v96
	ds_write2_b32 v82, v81, v80 offset0:40 offset1:172
	v_cndmask_b32_e64 v80, v109, v95, s[4:5]
	v_cndmask_b32_e64 v81, v110, v102, s[4:5]
	v_cndmask_b32_e32 v80, v81, v80, vcc
	v_fmamk_f32 v81, v88, 0xbdb8aa3b, v80
	v_fmamk_f32 v82, v88, 0x3db8aa3b, v81
	v_sub_f32_e32 v82, v91, v82
	v_cndmask_b32_e64 v81, v82, v81, s[60:61]
	v_add_f32_e32 v82, v100, v80
	v_fmamk_f32 v83, v89, 0x3db8aa3b, v82
	v_sub_f32_e32 v83, v91, v83
	v_cndmask_b32_e64 v82, v83, v82, s[60:61]
	v_add_u32_e32 v83, 0x2000, v96
	ds_write2_b32 v83, v81, v82 offset0:64 offset1:196
	v_add_f32_e32 v81, v172, v80
	v_fmamk_f32 v82, v101, 0x3db8aa3b, v81
	v_sub_f32_e32 v82, v91, v82
	v_add_f32_e32 v80, v173, v80
	v_cndmask_b32_e64 v81, v82, v81, s[60:61]
	v_fmamk_f32 v82, v162, 0x3db8aa3b, v80
	v_sub_f32_e32 v82, v91, v82
	v_cndmask_b32_e64 v80, v82, v80, s[60:61]
	v_add_u32_e32 v82, 0x2400, v96
	ds_write2_b32 v82, v81, v80 offset0:72 offset1:204
	v_cndmask_b32_e64 v80, v111, v103, s[4:5]
	v_cndmask_b32_e64 v81, v160, v104, s[4:5]
	v_cndmask_b32_e32 v80, v81, v80, vcc
	v_fmamk_f32 v81, v163, 0xbdb8aa3b, v80
	v_fmamk_f32 v82, v163, 0x3db8aa3b, v81
	v_sub_f32_e32 v82, v91, v82
	v_cndmask_b32_e64 v81, v82, v81, s[60:61]
	v_add_f32_e32 v82, v165, v80
	v_fmamk_f32 v83, v164, 0x3db8aa3b, v82
	v_sub_f32_e32 v83, v91, v83
	v_cndmask_b32_e64 v82, v83, v82, s[60:61]
	v_add_u32_e32 v83, 0x3000, v96
	ds_write2_b32 v83, v81, v82 offset0:96 offset1:228
	v_add_f32_e32 v81, v174, v80
	v_fmamk_f32 v82, v166, 0x3db8aa3b, v81
	v_sub_f32_e32 v82, v91, v82
	v_add_f32_e32 v80, v175, v80
	v_cndmask_b32_e64 v81, v82, v81, s[60:61]
	v_fmamk_f32 v82, v167, 0x3db8aa3b, v80
	v_sub_f32_e32 v82, v91, v82
	v_cndmask_b32_e64 v80, v82, v80, s[60:61]
	v_add_u32_e32 v82, 0x3400, v96
	s_and_b64 s[34:35], s[4:5], vcc
	ds_write2_b32 v82, v81, v80 offset0:104 offset1:236
	s_and_saveexec_b64 s[6:7], s[34:35]
	s_cbranch_execz .LBB0_525
	v_exp_f32_e32 v80, v91
	v_add_u32_e32 v81, 0x1e400, v90
	ds_write_b32 v81, v80

; #define LAS __attribute__((address_space(3)))
; #define LAUNDER(t) const int t = opaque_tid(wv)
; __device__ __forceinline__ void phase_scan(const bf16_t* QK, const bf16_t* V, const float* GLR, bf16_t* OFW, const float* wgate, const float* bgate, char* lds, int wv,
;                                            bf16_t* Z, const float* gn, unsigned long long* X, unsigned tag) {
;     ...
;                 { LAUNDER(t); const int fr = t & 15, fq = (t >> 4) & 3;
; #pragma unroll
;                   for (int tt = 0; tt < 2; ++tt) { const int tl = wid * 2 + tt, it = tl >> 2, jt = tl & 3;
;                     f32x4 pc = {0.f, 0.f, 0.f, 0.f};
;                     bf16x8 af[4], bfg[4];
; #pragma unroll
;                     for (int ks = 0; ks < 4; ++ks) {
;                         af[ks] = *(const bf16x8*)(lds + OFF_KE + (jt * 16 + fr) * KE_ST + (ks * 32 + fq * 8) * 2);
;                         bfg[ks] = *(const bf16x8*)(lds + OFF_QE + (it * 16 + fr) * QE_ST + (ks * 32 + fq * 8) * 2); }
;                     asm volatile("s_waitcnt lgkmcnt(0)" ::: "memory"); SCB(1);
; #pragma unroll
;                     for (int ks = 0; ks < 4; ++ks) pc = __builtin_amdgcn_mfma_f32_16x16x32_bf16(af[ks], bfg[ks], pc, 0, 0, 0);
;                     const int ii = it * 16 + fr, j0 = jt * 16 + fq * 4;
;                     float pm[4];
; #pragma unroll
;                     for (int e = 0; e < 4; ++e) pm[e] = (dir == 0 ? (j0 + e <= ii) : (j0 + e >= ii)) ? pc[e] : 0.f;
;                     u32x2 pw = {cvt_pk_bf16(pm[0], pm[1]), cvt_pk_bf16(pm[2], pm[3])};
;                     *(u32x2*)(lds + OFF_P + ii * P_ST + j0 * 2) = pw; } }
;                 bf16x8 vf[4];
;                 f32x16 o0 = f32x16{}, o1 = f32x16{};
;                 {
;                     LAUNDER(t); const int ln = t & 63, hi = ln >> 5, r32 = ln & 31, m16 = ln & 15, g16 = (ln >> 4) & 1;
;                     const int ldsb = (int)(uintptr_t)(LAS char*)lds;
;                     const int trv = ldsb + OFF_V + (8 * hi + (m16 >> 2)) * V_ST + (wid * 32 + 16 * g16 + 4 * (m16 & 3)) * 2;
;                     const int trk = ldsb + OFF_KE + (8 * hi + (m16 >> 2)) * KE_ST + (16 * g16 + 4 * (m16 & 3)) * 2;
;                     {
;                     const s16x4 l0 = tr_read<0 * 16 * V_ST>(trv), h0 = tr_read<0 * 16 * V_ST + 4 * V_ST>(trv), l1 = tr_read<1 * 16 * V_ST>(trv), h1 = tr_read<1 * 16 * V_ST + 4 * V_ST>(trv);
.LBB0_529:
	v_mov_b32_e32 v80, v233
	s_waitcnt lgkmcnt(0)
	s_barrier
	s_nop 0
	v_and_b32_e32 v88, 15, v80
	v_bfe_u32 v80, v80, 4, 2
	v_lshlrev_b32_e32 v89, 4, v80
	v_or_b32_e32 v84, s54, v88
	v_lshlrev_b32_e32 v86, 2, v80
	v_or_b32_e32 v80, s41, v88
	v_mul_lo_u32 v81, v84, s74
	v_mul_u32_u24_e32 v80, 0x140, v80
	v_add_u32_e32 v85, 0, v81
	v_add3_u32 v106, 0, v80, v89
	v_add_u32_e32 v87, v85, v89
	ds_read_b128 v[80:83], v106 offset:17408
	ds_read_b128 v[90:93], v106 offset:17472
	ds_read_b128 v[94:97], v87
	ds_read_b128 v[98:101], v87 offset:64
	ds_read_b128 v[102:105], v106 offset:17536
	ds_read_b128 v[106:109], v106 offset:17600
	ds_read_b128 v[160:163], v87 offset:128
	ds_read_b128 v[164:167], v87 offset:192
	s_waitcnt lgkmcnt(0)
	s_waitcnt lgkmcnt(5)
	v_mfma_f32_16x16x32_bf16 v[80:83], v[80:83], v[94:97], 0
	s_and_b64 vcc, exec, s[70:71]
	s_waitcnt lgkmcnt(4)
	v_mfma_f32_16x16x32_bf16 v[80:83], v[90:93], v[98:101], v[80:83]
	v_or_b32_e32 v90, s41, v86
	s_waitcnt lgkmcnt(1)
	v_mfma_f32_16x16x32_bf16 v[80:83], v[102:105], v[160:163], v[80:83]
	s_waitcnt lgkmcnt(0)
	v_mfma_f32_16x16x32_bf16 v[80:83], v[106:109], v[164:167], v[80:83]
	s_not_b64 s[6:7], s[70:71]
	s_cmp_lg_u64 s[70:71], 0
	v_cmp_le_u32_e32 vcc, v90, v84
	v_cmp_ge_u32_e64 s[34:35], v90, v84
	s_cselect_b64 s[62:63], s[34:35], vcc
	v_or_b32_e32 v91, 1, v90
	v_cmp_le_u32_e32 vcc, v91, v84
	v_cmp_ge_u32_e64 s[34:35], v91, v84
	s_cselect_b64 vcc, s[34:35], vcc
	s_nop 0
	v_cndmask_b32_e64 v91, 0, v80, s[62:63]
	v_cndmask_b32_e64 v80, 0, v81, vcc
	v_or_b32_e32 v81, 2, v90
	v_cmp_le_u32_e32 vcc, v81, v84
	v_cmp_ge_u32_e64 s[34:35], v81, v84
	s_cselect_b64 vcc, s[34:35], vcc
	v_cndmask_b32_e64 v81, 0, v82, vcc
	v_or_b32_e32 v82, 3, v90
	v_cmp_le_u32_e32 vcc, v82, v84
	v_cmp_ge_u32_e64 s[34:35], v82, v84
	s_cselect_b64 vcc, s[34:35], vcc
	v_cndmask_b32_e64 v82, 0, v83, vcc
	v_lshlrev_b32_e32 v83, 7, v84
	v_sub_u32_e32 v85, v85, v83
	v_cvt_pk_bf16_f32 v80, v91, v80
	v_cvt_pk_bf16_f32 v81, v81, v82
	v_lshl_add_u32 v82, v90, 1, v85
	ds_write_b64 v82, v[80:81] offset:37888
	v_or_b32_e32 v80, s94, v88
	v_mul_u32_u24_e32 v80, 0x140, v80
	v_add3_u32 v104, 0, v80, v89
	ds_read_b128 v[80:83], v104 offset:17408
	ds_read_b128 v[88:91], v104 offset:17472
	ds_read_b128 v[92:95], v87
	ds_read_b128 v[96:99], v87 offset:64
	ds_read_b128 v[100:103], v104 offset:17536
	ds_read_b128 v[104:107], v104 offset:17600
	ds_read_b128 v[108:111], v87 offset:128
	ds_read_b128 v[160:163], v87 offset:192
	s_waitcnt lgkmcnt(0)
	s_waitcnt lgkmcnt(5)
	v_mfma_f32_16x16x32_bf16 v[80:83], v[80:83], v[92:95], 0
	v_or_b32_e32 v86, s94, v86
	s_and_b64 vcc, exec, s[6:7]
	s_waitcnt lgkmcnt(4)
	v_mfma_f32_16x16x32_bf16 v[80:83], v[88:91], v[96:99], v[80:83]
	s_waitcnt lgkmcnt(1)
	v_mfma_f32_16x16x32_bf16 v[80:83], v[100:103], v[108:111], v[80:83]
	s_waitcnt lgkmcnt(0)
	v_mfma_f32_16x16x32_bf16 v[80:83], v[104:107], v[160:163], v[80:83]
	s_cmp_lg_u64 s[70:71], 0
	v_cmp_le_u32_e32 vcc, v86, v84
	v_cmp_ge_u32_e64 s[34:35], v86, v84
	s_cselect_b64 s[62:63], s[34:35], vcc
	v_or_b32_e32 v87, 1, v86
	v_cmp_le_u32_e32 vcc, v87, v84
	v_cmp_ge_u32_e64 s[34:35], v87, v84
	s_cselect_b64 vcc, s[34:35], vcc
	s_nop 1
	v_cndmask_b32_e64 v87, 0, v80, s[62:63]
	v_cndmask_b32_e64 v80, 0, v81, vcc
	v_or_b32_e32 v81, 2, v86
	v_cmp_le_u32_e32 vcc, v81, v84
	v_cmp_ge_u32_e64 s[34:35], v81, v84
	s_cselect_b64 vcc, s[34:35], vcc
	v_cndmask_b32_e64 v81, 0, v82, vcc
	v_or_b32_e32 v82, 3, v86
	v_cmp_le_u32_e32 vcc, v82, v84
	v_cmp_ge_u32_e64 s[34:35], v82, v84
	s_cselect_b64 vcc, s[34:35], vcc
	v_cndmask_b32_e64 v82, 0, v83, vcc
	v_cvt_pk_bf16_f32 v80, v87, v80
	v_cvt_pk_bf16_f32 v81, v81, v82
	v_lshl_add_u32 v82, v86, 1, v85
	ds_write_b64 v82, v[80:81] offset:37888
	v_mov_b32_e32 v80, v233
	s_add_i32 s34, 0, 0xb800
	v_bfe_u32 v200, v80, 5, 1
	v_and_b32_e32 v81, 31, v80
	v_and_b32_e32 v82, 16, v80
	v_lshrrev_b32_e32 v84, 2, v80
	v_lshlrev_b32_e32 v80, 2, v80
	v_lshlrev_b32_e32 v83, 3, v200
	v_and_b32_e32 v80, 12, v80
	v_and_or_b32 v201, v84, 3, v83
	v_or3_b32 v85, s52, v82, v80
	v_mul_u32_u24_e32 v84, 0x240, v201
	v_lshlrev_b32_e32 v85, 1, v85
	v_add3_u32 v84, v85, s34, v84
	ds_read_b64_tr_b16 v[172:173], v84 offset:0
	ds_read_b64_tr_b16 v[174:175], v84 offset:0x900
	ds_read_b64_tr_b16 v[168:169], v84 offset:0x2400
	ds_read_b64_tr_b16 v[170:171], v84 offset:0x2d00
	ds_read_b64_tr_b16 v[164:165], v84 offset:0x4800
	ds_read_b64_tr_b16 v[166:167], v84 offset:0x5100
	ds_read_b64_tr_b16 v[160:161], v84 offset:0x6c00
	ds_read_b64_tr_b16 v[162:163], v84 offset:0x7500
	s_waitcnt lgkmcnt(0)
	v_or_b32_e32 v80, v80, v82
	v_lshlrev_b32_e32 v202, 1, v80
	v_mul_u32_u24_e32 v80, 0x110, v81
	v_add3_u32 v203, 0, v80, v83
	v_add_u32_e32 v204, 0x2000, v203
	ds_read2_b64 v[80:83], v204 offset0:64 offset1:66
	ds_read2_b64 v[84:87], v203 offset1:2
	ds_read2_b64 v[176:179], v203 offset0:4 offset1:6
	ds_read2_b64 v[180:183], v204 offset0:68 offset1:70
	v_cvt_pk_bf16_f32 v88, v16, v17
	v_cvt_pk_bf16_f32 v89, v18, v19
	v_cvt_pk_bf16_f32 v90, v20, v21
	v_cvt_pk_bf16_f32 v91, v22, v23
	v_cvt_pk_bf16_f32 v184, v24, v25
	v_cvt_pk_bf16_f32 v185, v26, v27
	v_cvt_pk_bf16_f32 v186, v28, v29
	v_cvt_pk_bf16_f32 v187, v30, v31
	s_waitcnt lgkmcnt(0)
	s_waitcnt lgkmcnt(2)
	v_mfma_f32_32x32x16_bf16 v[96:111], v[84:87], v[88:91], 0
	v_mfma_f32_32x32x16_bf16 v[80:95], v[80:83], v[88:91], 0
	s_waitcnt lgkmcnt(1)
	v_mfma_f32_32x32x16_bf16 v[96:111], v[176:179], v[184:187], v[96:111]
	s_waitcnt lgkmcnt(0)
; __device__ __forceinline__ unsigned cvt_pk_bf16(float lo, float hi) { unsigned r; asm volatile("v_cvt_pk_bf16_f32 %0, %1, %2" : "=v"(r) : "v"(lo), "v"(hi)); return r; }
; #define SCB(i) do { if (SC_MASK & (1 << (i))) __builtin_amdgcn_sched_barrier(0); } while (0)
; __device__ __forceinline__ void phase_scan(const bf16_t* QK, const bf16_t* V, const float* GLR, bf16_t* OFW, const float* wgate, const float* bgate, char* lds, int wv,
;                                            bf16_t* Z, const float* gn, unsigned long long* X, unsigned tag) {
;     ...
;                     const char* qa = lds + OFF_QE + r32 * QE_ST + 8 * hi;
; #pragma unroll
;                     for (int db = 0; db < 4; ++db) {
;                         s16x4 al[2][2], ah[2][2];
; #pragma unroll
;                         for (int s = 0; s < 2; ++s) { const int dcol = (db * 32 + 16 * s) * 2;
;                             al[s][0] = *(const s16x4*)(qa + dcol); ah[s][0] = *(const s16x4*)(qa + dcol + 16);
;                             al[s][1] = *(const s16x4*)(qa + 32 * QE_ST + dcol); ah[s][1] = *(const s16x4*)(qa + 32 * QE_ST + dcol + 16); }
;                         bf16x8 bfr[2];
; #pragma unroll
;                         for (int s = 0; s < 2; ++s) {
;                             u32x4 bw = {cvt_pk_bf16(S[db][8 * s + 0], S[db][8 * s + 1]), cvt_pk_bf16(S[db][8 * s + 2], S[db][8 * s + 3]),
;                                         cvt_pk_bf16(S[db][8 * s + 4], S[db][8 * s + 5]), cvt_pk_bf16(S[db][8 * s + 6], S[db][8 * s + 7])};
;                             bfr[s] = *reinterpret_cast<bf16x8*>(&bw); }
;                         asm volatile("s_waitcnt lgkmcnt(0)" ::: "memory"); SCB(3);
; #pragma unroll
;                         for (int s = 0; s < 2; ++s) {
;                             o0 = __builtin_amdgcn_mfma_f32_32x32x16_bf16(PK8(al[s][0], ah[s][0]), bfr[s], o0, 0, 0, 0);
;                             o1 = __builtin_amdgcn_mfma_f32_32x32x16_bf16(PK8(al[s][1], ah[s][1]), bfr[s], o1, 0, 0, 0); }
;                     }
;                     const char* ebp = lds + OFF_EBT + 16 * hi;
;     ...
;                     SUPD(0); SUPD(1); SUPD(2); SUPD(3);
	v_mfma_f32_32x32x16_bf16 v[80:95], v[180:183], v[184:187], v[80:95]
	ds_read2_b64 v[176:179], v204 offset0:72 offset1:74
	ds_read2_b64 v[180:183], v203 offset0:8 offset1:10
	ds_read2_b64 v[184:187], v203 offset0:12 offset1:14
	ds_read2_b64 v[188:191], v204 offset0:76 offset1:78
	v_cvt_pk_bf16_f32 v192, v32, v33
	v_cvt_pk_bf16_f32 v193, v34, v35
	v_cvt_pk_bf16_f32 v194, v36, v37
	v_cvt_pk_bf16_f32 v195, v38, v39
	v_cvt_pk_bf16_f32 v196, v40, v41
	v_cvt_pk_bf16_f32 v197, v42, v43
	v_cvt_pk_bf16_f32 v198, v44, v45
	v_cvt_pk_bf16_f32 v199, v46, v47
	s_waitcnt lgkmcnt(0)
	s_waitcnt lgkmcnt(2)
	v_mfma_f32_32x32x16_bf16 v[96:111], v[180:183], v[192:195], v[96:111]
	v_mfma_f32_32x32x16_bf16 v[80:95], v[176:179], v[192:195], v[80:95]
	s_waitcnt lgkmcnt(1)
	v_mfma_f32_32x32x16_bf16 v[96:111], v[184:187], v[196:199], v[96:111]
	s_waitcnt lgkmcnt(0)
	v_mfma_f32_32x32x16_bf16 v[80:95], v[188:191], v[196:199], v[80:95]
	ds_read2_b64 v[176:179], v204 offset0:80 offset1:82
	ds_read2_b64 v[180:183], v203 offset0:16 offset1:18
	ds_read2_b64 v[184:187], v203 offset0:20 offset1:22
	ds_read2_b64 v[188:191], v204 offset0:84 offset1:86
	v_cvt_pk_bf16_f32 v192, v48, v49
	v_cvt_pk_bf16_f32 v193, v50, v51
	v_cvt_pk_bf16_f32 v194, v52, v53
	v_cvt_pk_bf16_f32 v195, v54, v55
	v_cvt_pk_bf16_f32 v196, v56, v57
	v_cvt_pk_bf16_f32 v197, v58, v59
	v_cvt_pk_bf16_f32 v198, v60, v61
	v_cvt_pk_bf16_f32 v199, v62, v63
	s_waitcnt lgkmcnt(0)
	s_waitcnt lgkmcnt(2)
	v_mfma_f32_32x32x16_bf16 v[96:111], v[180:183], v[192:195], v[96:111]
	v_mfma_f32_32x32x16_bf16 v[80:95], v[176:179], v[192:195], v[80:95]
	s_waitcnt lgkmcnt(1)
	v_mfma_f32_32x32x16_bf16 v[96:111], v[184:187], v[196:199], v[96:111]
	s_waitcnt lgkmcnt(0)
	v_mfma_f32_32x32x16_bf16 v[80:95], v[188:191], v[196:199], v[80:95]
	ds_read2_b64 v[184:187], v204 offset0:88 offset1:90
	ds_read2_b64 v[188:191], v203 offset0:24 offset1:26
	ds_read2_b64 v[192:195], v203 offset0:28 offset1:30
	ds_read2_b64 v[176:179], v204 offset0:92 offset1:94
	v_cvt_pk_bf16_f32 v196, v64, v65
	v_cvt_pk_bf16_f32 v197, v66, v67
	v_cvt_pk_bf16_f32 v198, v68, v69
	v_cvt_pk_bf16_f32 v199, v70, v71
	v_cvt_pk_bf16_f32 v180, v72, v73
	v_cvt_pk_bf16_f32 v181, v74, v75
	v_cvt_pk_bf16_f32 v182, v76, v77
	v_cvt_pk_bf16_f32 v183, v78, v79
	s_waitcnt lgkmcnt(0)
	v_mul_u32_u24_e32 v201, 0x140, v201
	v_lshl_add_u32 v200, v200, 4, 0
	v_add3_u32 v212, v202, s67, v201
	v_add_u32_e32 v214, 0x1e400, v200
	ds_read_b64_tr_b16 v[200:201], v212 offset:0
	ds_read_b64_tr_b16 v[202:203], v212 offset:0x500
	ds_read_b64_tr_b16 v[204:205], v212 offset:0x1400
	ds_read_b64_tr_b16 v[206:207], v212 offset:0x1900
	ds_read_b64_tr_b16 v[208:209], v212 offset:0x2800
	ds_read_b64_tr_b16 v[210:211], v212 offset:0x2d00
	ds_read_b64_tr_b16 v[246:247], v212 offset:0x3c00
	ds_read_b64_tr_b16 v[248:249], v212 offset:0x4100
	s_waitcnt lgkmcnt(0)
	s_nop 0
	v_mfma_f32_32x32x16_bf16 v[16:31], v[200:203], v[172:175], v[16:31]
	v_mfma_f32_32x32x16_bf16 v[16:31], v[204:207], v[168:171], v[16:31]
	v_mfma_f32_32x32x16_bf16 v[16:31], v[208:211], v[164:167], v[16:31]
	v_mfma_f32_32x32x16_bf16 v[16:31], v[246:249], v[160:163], v[16:31]
	ds_read_b128 v[200:203], v214
	ds_read_b128 v[204:207], v214 offset:32
	ds_read_b128 v[208:211], v214 offset:64
	ds_read_b128 v[246:249], v214 offset:96
	s_waitcnt lgkmcnt(6)
	v_mfma_f32_32x32x16_bf16 v[96:111], v[188:191], v[196:199], v[96:111]
	s_waitcnt lgkmcnt(0)
	s_nop 4
	v_mul_f32_e64 v30, v30, v248
	v_mul_f32_e64 v31, v31, v249
	v_mul_f32_e64 v28, v28, v246
	v_mul_f32_e64 v29, v29, v247
	v_pk_mul_f32 v[26:27], v[26:27], v[210:211]
	v_pk_mul_f32 v[24:25], v[24:25], v[208:209]
	v_pk_mul_f32 v[22:23], v[22:23], v[206:207]
	v_pk_mul_f32 v[20:21], v[20:21], v[204:205]
	v_pk_mul_f32 v[18:19], v[18:19], v[202:203]
	v_pk_mul_f32 v[16:17], v[16:17], v[200:201]
	v_mfma_f32_32x32x16_bf16 v[96:111], v[192:195], v[180:183], v[96:111]
	ds_read_b64_tr_b16 v[188:189], v212 offset:64
	ds_read_b64_tr_b16 v[190:191], v212 offset:0x540
	ds_read_b64_tr_b16 v[192:193], v212 offset:0x1440
	ds_read_b64_tr_b16 v[194:195], v212 offset:0x1940
	ds_read_b64_tr_b16 v[200:201], v212 offset:0x2840
	ds_read_b64_tr_b16 v[202:203], v212 offset:0x2d40
	ds_read_b64_tr_b16 v[204:205], v212 offset:0x3c40
	ds_read_b64_tr_b16 v[206:207], v212 offset:0x4140
	s_waitcnt lgkmcnt(0)
	s_nop 0
	v_mfma_f32_32x32x16_bf16 v[32:47], v[188:191], v[172:175], v[32:47]
	v_mfma_f32_32x32x16_bf16 v[32:47], v[192:195], v[168:171], v[32:47]
	v_mfma_f32_32x32x16_bf16 v[32:47], v[200:203], v[164:167], v[32:47]
	v_mfma_f32_32x32x16_bf16 v[32:47], v[204:207], v[160:163], v[32:47]
	ds_read_b128 v[188:191], v214 offset:128
	ds_read_b128 v[192:195], v214 offset:160
	ds_read_b128 v[200:203], v214 offset:192
	ds_read_b128 v[204:207], v214 offset:224
	v_mfma_f32_32x32x16_bf16 v[80:95], v[184:187], v[196:199], v[80:95]
	s_waitcnt lgkmcnt(0)
; #define LBAR() do { asm volatile("s_waitcnt lgkmcnt(0)" ::: "memory"); __builtin_amdgcn_s_barrier(); asm volatile("" ::: "memory"); } while (0)
; #define STAGE_VG() do { LAUNDER(t_); const int vr = t_ >> 5, vc = (t_ & 31) * 8, gr = t_ >> 3, gc = (t_ & 7) * 2; \
;     _Pragma("unroll") for (int i = 0; i < 4; ++i) *(bf16x8*)(lds + OFF_V + (vr + 16 * i) * V_ST + vc * 2) = rv[i]; \
;     *(f32x2*)(lds + OFF_GLR + gr * 64 + gc * 4) = rg; } while (0)
; __device__ __forceinline__ void phase_scan(const bf16_t* QK, const bf16_t* V, const float* GLR, bf16_t* OFW, const float* wgate, const float* bgate, char* lds, int wv,
;                                            bf16_t* Z, const float* gn, unsigned long long* X, unsigned tag) {
;     ...
;                     SUPD(0); SUPD(1); SUPD(2); SUPD(3);
;     ...
;                 }
;                 LBAR();
;                 if (step + 1 < 32) { STAGE_VG(); if (step + 2 < 32) { const int nn = dir == 0 ? step + 2 : 29 - step; CLOAD_VG(nn); } }
	s_nop 5
	v_mul_f32_e64 v46, v46, v206
	v_mul_f32_e64 v47, v47, v207
	v_mul_f32_e64 v44, v44, v204
	v_mul_f32_e64 v45, v45, v205
	v_pk_mul_f32 v[42:43], v[42:43], v[202:203]
	v_pk_mul_f32 v[40:41], v[40:41], v[200:201]
	v_pk_mul_f32 v[38:39], v[38:39], v[194:195]
	v_pk_mul_f32 v[36:37], v[36:37], v[192:193]
	v_pk_mul_f32 v[34:35], v[34:35], v[190:191]
	v_pk_mul_f32 v[32:33], v[32:33], v[188:189]
	s_nop 0
	ds_read_b64_tr_b16 v[184:185], v212 offset:0x80
	ds_read_b64_tr_b16 v[186:187], v212 offset:0x580
	ds_read_b64_tr_b16 v[188:189], v212 offset:0x1480
	ds_read_b64_tr_b16 v[190:191], v212 offset:0x1980
	ds_read_b64_tr_b16 v[192:193], v212 offset:0x2880
	ds_read_b64_tr_b16 v[194:195], v212 offset:0x2d80
	ds_read_b64_tr_b16 v[196:197], v212 offset:0x3c80
	ds_read_b64_tr_b16 v[198:199], v212 offset:0x4180
	s_waitcnt lgkmcnt(0)
	s_nop 0
	v_mfma_f32_32x32x16_bf16 v[48:63], v[184:187], v[172:175], v[48:63]
	v_mfma_f32_32x32x16_bf16 v[48:63], v[188:191], v[168:171], v[48:63]
	v_mfma_f32_32x32x16_bf16 v[48:63], v[192:195], v[164:167], v[48:63]
	v_mfma_f32_32x32x16_bf16 v[48:63], v[196:199], v[160:163], v[48:63]
	ds_read_b128 v[184:187], v214 offset:256
	ds_read_b128 v[188:191], v214 offset:288
	ds_read_b128 v[192:195], v214 offset:320
	ds_read_b128 v[196:199], v214 offset:352
	s_waitcnt lgkmcnt(0)
	s_nop 6
	v_pk_mul_f32 v[62:63], v[62:63], v[198:199]
	v_pk_mul_f32 v[60:61], v[60:61], v[196:197]
	v_pk_mul_f32 v[58:59], v[58:59], v[194:195]
	v_pk_mul_f32 v[56:57], v[56:57], v[192:193]
	v_pk_mul_f32 v[54:55], v[54:55], v[190:191]
	v_pk_mul_f32 v[52:53], v[52:53], v[188:189]
	v_pk_mul_f32 v[50:51], v[50:51], v[186:187]
	v_pk_mul_f32 v[48:49], v[48:49], v[184:185]
	s_nop 0
	ds_read_b64_tr_b16 v[184:185], v212 offset:0xc0
	ds_read_b64_tr_b16 v[186:187], v212 offset:0x5c0
	ds_read_b64_tr_b16 v[188:189], v212 offset:0x14c0
	ds_read_b64_tr_b16 v[190:191], v212 offset:0x19c0
	ds_read_b64_tr_b16 v[192:193], v212 offset:0x28c0
	ds_read_b64_tr_b16 v[194:195], v212 offset:0x2dc0
	ds_read_b64_tr_b16 v[196:197], v212 offset:0x3cc0
	ds_read_b64_tr_b16 v[198:199], v212 offset:0x41c0
	s_waitcnt lgkmcnt(0)
	s_nop 0
	v_mfma_f32_32x32x16_bf16 v[64:79], v[184:187], v[172:175], v[64:79]
	s_andn2_b64 vcc, exec, s[8:9]
	v_mfma_f32_32x32x16_bf16 v[64:79], v[188:191], v[168:171], v[64:79]
	v_mfma_f32_32x32x16_bf16 v[64:79], v[192:195], v[164:167], v[64:79]
	v_mfma_f32_32x32x16_bf16 v[64:79], v[196:199], v[160:163], v[64:79]
	ds_read_b128 v[184:187], v214 offset:384
	ds_read_b128 v[188:191], v214 offset:416
	ds_read_b128 v[192:195], v214 offset:448
	ds_read_b128 v[196:199], v214 offset:480
	v_mfma_f32_32x32x16_bf16 v[80:95], v[176:179], v[180:183], v[80:95]
	s_waitcnt lgkmcnt(0)
	s_nop 5
	v_mul_f32_e64 v78, v78, v198
	v_mul_f32_e64 v79, v79, v199
	v_mul_f32_e64 v76, v76, v196
	v_mul_f32_e64 v77, v77, v197
	v_pk_mul_f32 v[74:75], v[74:75], v[194:195]
	v_pk_mul_f32 v[72:73], v[72:73], v[192:193]
	v_pk_mul_f32 v[70:71], v[70:71], v[190:191]
	v_pk_mul_f32 v[68:69], v[68:69], v[188:189]
	v_pk_mul_f32 v[66:67], v[66:67], v[186:187]
	v_pk_mul_f32 v[64:65], v[64:65], v[184:185]
	s_nop 0
	s_waitcnt lgkmcnt(0)
	s_barrier
	s_cbranch_vccnz .LBB0_580
	v_mov_b32_e32 v176, v233
	s_cmp_gt_u32 s85, 29
	v_add_u32_e32 v177, s75, v176
	v_lshrrev_b32_e32 v178, 5, v177
	v_lshlrev_b32_e32 v176, 4, v176
	v_and_b32_e32 v176, 0x1f0, v176
	v_mul_lo_u32 v178, v178, s33
	v_lshlrev_b32_e32 v177, 3, v177
	v_add3_u32 v176, 0, v176, v178
	v_add_u32_e32 v178, 0xb800, v176
	s_waitcnt vmcnt(4)
	ds_write_b128 v176, v[144:147] offset:47104
	s_waitcnt vmcnt(3)
	ds_write_b128 v176, v[148:151] offset:56320
	s_waitcnt vmcnt(2)
	ds_write_b128 v178, v[152:155] offset:18432
	s_waitcnt vmcnt(1)
	ds_write_b128 v178, v[156:159] offset:27648
	v_and_b32_e32 v176, 56, v177
	v_and_b32_e32 v177, 0xffffffc0, v177
	v_add3_u32 v176, s3, v177, v176
	s_waitcnt vmcnt(0)
	ds_write_b64 v176, v[224:225]
	s_cbranch_scc1 .LBB0_580
	s_add_i32 s34, s85, 2
	s_sub_i32 s35, 29, s85
	s_and_b64 s[8:9], s[60:61], exec
	s_cselect_b32 s8, s34, s35
	s_lshl_b32 s8, s8, 6
	s_add_u32 s8, s22, s8
	v_mov_b32_e32 v144, v233
	s_addc_u32 s9, s23, 0
	s_lshl_b64 s[34:35], s[8:9], 12
	v_add_u32_e32 v145, s75, v144
	v_lshlrev_b32_e32 v158, 4, v145
	s_or_b32 s34, s34, s97
	v_lshlrev_b32_e32 v146, 7, v145
	v_and_b32_e32 v145, 0x1f0, v158
	s_add_u32 s34, s64, s34
	v_and_or_b32 v212, v146, s84, v145
	s_addc_u32 s35, s65, s35
	v_lshl_add_u64 v[156:157], s[34:35], 0, v[212:213]
	v_add_co_u32_e32 v148, vcc, 0x10000, v156
	v_lshlrev_b32_e32 v144, 3, v144
	s_nop 0
	v_addc_co_u32_e32 v149, vcc, 0, v157, vcc
	v_add_co_u32_e32 v152, vcc, 0x20000, v156
	s_lshl_b64 s[8:9], s[8:9], 7
	s_nop 0
	v_addc_co_u32_e32 v153, vcc, 0, v157, vcc
	v_add_co_u32_e32 v156, vcc, 0x30000, v156
	v_and_b32_e32 v159, 56, v144
	s_nop 0
	v_addc_co_u32_e32 v157, vcc, 0, v157, vcc
	s_add_u32 s8, s42, s8
	global_load_dwordx4 v[144:147], v212, s[34:35]
	s_nop 0
	global_load_dwordx4 v[148:151], v[148:149], off
	s_nop 0
	global_load_dwordx4 v[152:155], v[152:153], off
	v_and_or_b32 v176, v158, s82, v159
	s_addc_u32 s9, s2, s9
	global_load_dwordx4 v[156:159], v[156:157], off
	s_nop 0
	global_load_dwordx2 v[224:225], v176, s[8:9]
